# sample FoX units: 16 cache loads in flight per staging step (hand-written regular-tile path); conv stores as whole lines
# baseline (speedup 1.0000x reference)
; #define ATT_LDS_WAIT() asm volatile("s_waitcnt lgkmcnt(0)" ::: "memory")
; template <int TYPE>
; __device__ __forceinline__ void sample_unit(const Args& a, int l, int b, int h, LAS unsigned char* lds) {
;     ...
;     for (int rnd = 0; rnd < 9; ++rnd) {
;         const int gidx = rnd * 8 + 7 - wid; const bool valid = gidx <= 64, isnew = gidx == 0; const int ct = 64 - gidx;
;         const float* ksrc = isnew ? kn : kc + (size_t)ct * 64 * W; const float* vsrc = isnew ? vn : vc + (size_t)ct * 64 * W;
;         const int nrows = isnew ? DT : 64;
;         if (TYPE == 0) {
;             if (valid) {
;                 ATT_LDS_WAIT();
;                 ATT_STAGE(ksrc, nrows, false); ATT_STAGE(vsrc, nrows, true);
;                 ATT_LDS_WAIT();
;                 const float* ckt = ckb + (isnew ? PAST : ct * 64) + 4 * hi;
;                 fox_tile(st, (lds_cptr)kreg, vp, qr, ckt, isnew, !started, qlim_new, r32, hi, wsf);
.LBB0_434:
	s_add_i32 s4, s63, s68
	s_cmp_gt_i32 s4, 64
	s_cbranch_scc1 .LBB0_433
	s_cmp_eq_u32 s4, 0
	s_cselect_b64 s[52:53], -1, 0
	s_cbranch_scc0 .Lsfast_l0
	s_and_b64 s[4:5], s[52:53], exec
	s_cselect_b32 s5, s60, s65
	s_cselect_b32 s4, s59, s64
	v_lshlrev_b32_e32 v4, 2, v112
	v_lshl_add_u64 v[164:165], s[4:5], 0, v[4:5]
	v_lshlrev_b32_e32 v78, 2, v116
	v_mov_b32_e32 v79, v5
	v_lshlrev_b32_e32 v82, 2, v118
	v_mov_b32_e32 v83, v5
	s_waitcnt lgkmcnt(0)
	v_lshl_add_u64 v[2:3], v[164:165], 0, v[78:79]
	v_lshl_add_u64 v[10:11], v[164:165], 0, v[82:83]
	v_lshlrev_b32_e32 v84, 2, v120
	v_mov_b32_e32 v85, v5
	global_load_dwordx4 v[58:61], v[2:3], off nt
	s_nop 0
	global_load_dwordx4 v[10:13], v[10:11], off nt
	v_lshl_add_u64 v[2:3], v[164:165], 0, v[84:85]
	v_lshlrev_b32_e32 v88, 2, v122
	v_mov_b32_e32 v89, v5
	v_lshl_add_u64 v[14:15], v[164:165], 0, v[88:89]
	global_load_dwordx4 v[62:65], v[2:3], off nt
	global_load_dwordx4 v[20:23], v[14:15], off nt
	s_cselect_b32 s33, 16, 64
	v_cmp_gt_u32_e32 vcc, s33, v133
	v_mov_b32_e32 v14, 0
	v_lshlrev_b32_e32 v2, 2, v124
	v_mov_b32_e32 v66, 0
	v_mov_b32_e32 v67, 0
	v_mov_b32_e32 v68, 0
	v_mov_b32_e32 v69, 0
	s_and_saveexec_b64 s[4:5], vcc
	s_cbranch_execz .LBB0_437
	v_mov_b32_e32 v3, v5
	v_lshl_add_u64 v[16:17], v[164:165], 0, v[2:3]
	global_load_dwordx4 v[66:69], v[16:17], off nt

; __device__ __forceinline__ int crow(int r, int hi) { return (r & 3) + 8 * (r >> 2) + 4 * hi; }
;     bf16x8 kf[8]; kfrags(kf, kslot, r32, hi);
;     f32x16 p0, p1;
; #pragma unroll
;     for (int g = 0; g < 4; ++g) { const f32x4 c0 = ld4(ckt + 8 * g), c1 = ld4(ckt + 32 + 8 * g);
; #pragma unroll
;         for (int i = 0; i < 4; ++i) { p0[4 * g + i] = c0[i]; p1[4 * g + i] = c1[i]; } }
;     u32x4 kn = {0u, 0xBF800000u, 0xBF80BF80u, 0u}; if (hi) { kn.y = 0u; kn.z = 0u; }
;     const bf16x8 kneg = __builtin_bit_cast(bf16x8, kn);
;     p0 = __builtin_amdgcn_mfma_f32_32x32x16_bf16(kneg, st.mq, p0, 0, 0, 0);
;     p1 = __builtin_amdgcn_mfma_f32_32x32x16_bf16(kneg, st.mq, p1, 0, 0, 0);
; #pragma unroll
;     for (int d0 = 0; d0 < 4; ++d0) {
;         p0 = __builtin_amdgcn_mfma_f32_32x32x16_bf16(kf[2 * d0], qr[d0], p0, 0, 0, 0);
;         p1 = __builtin_amdgcn_mfma_f32_32x32x16_bf16(kf[2 * d0 + 1], qr[d0], p1, 0, 0, 0);
;     }
;     __builtin_amdgcn_sched_barrier(0);
;     if (LEVEL == 2) { asm volatile("" :: "v"(p0), "v"(p1)); return; }
;     if (masked) {
;         asm volatile("; masked tile" ::: "memory");
; #pragma unroll
;         for (int r = 0; r < 16; ++r) { const int kv = crow(r, hi); if (kv >= qlim) p0[r] = NEG; if (kv + 32 >= qlim) p1[r] = NEG; }
.Lsjoin_l0:
	s_ashr_i32 s49, s48, 31
	s_waitcnt lgkmcnt(0)
	v_lshl_add_u64 v[2:3], s[48:49], 2, v[114:115]
	global_load_dwordx4 v[74:77], v[2:3], off
	global_load_dwordx4 v[78:81], v[2:3], off offset:32
	global_load_dwordx4 v[82:85], v[2:3], off offset:64
	global_load_dwordx4 v[86:89], v[2:3], off offset:96
	global_load_dwordx4 v[58:61], v[2:3], off offset:128
	global_load_dwordx4 v[62:65], v[2:3], off offset:160
	global_load_dwordx4 v[66:69], v[2:3], off offset:192
	global_load_dwordx4 v[70:73], v[2:3], off offset:224
	ds_read_b128 v[10:13], v171
	s_waitcnt vmcnt(4)
	v_mfma_f32_32x32x16_bf16 v[74:89], v[90:93], v[6:9], v[74:89]
	s_waitcnt lgkmcnt(0)
	v_mfma_f32_32x32x16_bf16 v[74:89], v[10:13], v[94:97], v[74:89]
	ds_read_b128 v[10:13], v171 offset:512
	s_waitcnt vmcnt(0)
	v_mfma_f32_32x32x16_bf16 v[58:73], v[90:93], v[6:9], v[58:73]
	s_waitcnt lgkmcnt(0)
	v_mfma_f32_32x32x16_bf16 v[58:73], v[10:13], v[94:97], v[58:73]
	ds_read_b128 v[10:13], v171 offset:2048
	s_waitcnt lgkmcnt(0)
	v_mfma_f32_32x32x16_bf16 v[74:89], v[10:13], v[98:101], v[74:89]
	ds_read_b128 v[10:13], v171 offset:2560
	s_waitcnt lgkmcnt(0)
	v_mfma_f32_32x32x16_bf16 v[58:73], v[10:13], v[98:101], v[58:73]
	ds_read_b128 v[10:13], v171 offset:4096
	s_waitcnt lgkmcnt(0)
	v_mfma_f32_32x32x16_bf16 v[74:89], v[10:13], v[102:105], v[74:89]
	ds_read_b128 v[10:13], v171 offset:4608
	s_waitcnt lgkmcnt(0)
	v_mfma_f32_32x32x16_bf16 v[58:73], v[10:13], v[102:105], v[58:73]
	ds_read_b128 v[10:13], v171 offset:6144
	s_waitcnt lgkmcnt(0)
	v_mfma_f32_32x32x16_bf16 v[74:89], v[10:13], v[106:109], v[74:89]
	ds_read_b128 v[10:13], v171 offset:6656
	s_waitcnt lgkmcnt(0)
	v_mfma_f32_32x32x16_bf16 v[58:73], v[10:13], v[106:109], v[58:73]
	s_and_b64 vcc, exec, s[52:53]
	s_cbranch_vccz .LBB0_485
	s_nop 6
	v_cndmask_b32_e64 v2, v74, v18, s[8:9]
	v_cndmask_b32_e64 v2, v2, v74, s[10:11]
	v_cndmask_b32_e64 v3, v18, v75, s[10:11]
	v_mov_b32_e32 v24, v18
	v_mov_b32_e32 v25, v18
	v_cndmask_b32_e64 v17, v81, v18, s[12:13]
	v_cndmask_b32_e64 v11, v75, v3, s[22:23]
	v_cndmask_b32_e64 v10, v74, v2, s[22:23]
	v_cndmask_b32_e64 v16, v80, v18, s[14:15]
	v_cndmask_b32_e64 v15, v79, v18, s[16:17]
	v_cndmask_b32_e64 v14, v78, v18, s[18:19]
	v_cndmask_b32_e64 v13, v77, v18, s[20:21]
	v_cndmask_b32_e64 v12, v76, v18, s[22:23]
	v_mov_b32_e32 v19, v18
	v_mov_b32_e32 v20, v18
	v_mov_b32_e32 v21, v18
	v_mov_b32_e32 v22, v18
	v_mov_b32_e32 v23, v18
	v_mov_b64_e32 v[88:89], v[24:25]
	v_mov_b32_e32 v58, v18
	v_mov_b32_e32 v59, v18
	v_mov_b32_e32 v60, v18
	v_mov_b32_e32 v61, v18
	v_mov_b32_e32 v62, v18
	v_mov_b32_e32 v63, v18
	v_mov_b32_e32 v64, v18
	v_mov_b32_e32 v65, v18
	v_mov_b32_e32 v66, v18
	v_mov_b32_e32 v67, v18
	v_mov_b32_e32 v68, v18
	v_mov_b32_e32 v69, v18
	v_mov_b32_e32 v70, v18
	v_mov_b32_e32 v71, v18
	v_mov_b32_e32 v72, v18
	v_mov_b32_e32 v73, v18
	v_mov_b64_e32 v[86:87], v[22:23]
	v_mov_b64_e32 v[84:85], v[20:21]
	v_mov_b64_e32 v[82:83], v[18:19]
	v_mov_b64_e32 v[80:81], v[16:17]
	v_mov_b64_e32 v[78:79], v[14:15]
	v_mov_b64_e32 v[76:77], v[12:13]
	v_mov_b64_e32 v[74:75], v[10:11]

.Lsfast_l0:
	v_lshlrev_b32_e32 v4, 2, v112
	v_lshl_add_u64 v[164:165], s[64:65], 0, v[4:5]
	v_lshl_add_u64 v[78:79], s[66:67], 0, v[4:5]
	v_mov_b32_e32 v81, 0
	s_waitcnt lgkmcnt(0)
	v_lshlrev_b32_e32 v80, 2, v116
	v_lshl_add_u64 v[82:83], v[164:165], 0, v[80:81]
	global_load_dwordx4 v[58:61], v[82:83], off nt
	v_lshlrev_b32_e32 v80, 2, v118
	v_lshl_add_u64 v[82:83], v[164:165], 0, v[80:81]
	global_load_dwordx4 v[10:13], v[82:83], off nt
	v_lshlrev_b32_e32 v80, 2, v120
	v_lshl_add_u64 v[82:83], v[164:165], 0, v[80:81]
	global_load_dwordx4 v[62:65], v[82:83], off nt
	v_lshlrev_b32_e32 v80, 2, v122
	v_lshl_add_u64 v[82:83], v[164:165], 0, v[80:81]
	global_load_dwordx4 v[20:23], v[82:83], off nt
	v_lshlrev_b32_e32 v80, 2, v124
	v_lshl_add_u64 v[82:83], v[164:165], 0, v[80:81]
	global_load_dwordx4 v[66:69], v[82:83], off nt
	v_lshlrev_b32_e32 v80, 2, v126
	v_lshl_add_u64 v[82:83], v[164:165], 0, v[80:81]
	global_load_dwordx4 v[14:17], v[82:83], off nt
	v_lshlrev_b32_e32 v80, 2, v128
	v_lshl_add_u64 v[82:83], v[164:165], 0, v[80:81]
	global_load_dwordx4 v[74:77], v[82:83], off nt
	v_lshlrev_b32_e32 v80, 2, v130
	v_lshl_add_u64 v[82:83], v[164:165], 0, v[80:81]
	global_load_dwordx4 v[70:73], v[82:83], off nt
	v_lshlrev_b32_e32 v80, 2, v132
	v_lshl_add_u64 v[82:83], v[164:165], 0, v[80:81]
	global_load_dwordx4 v[196:199], v[82:83], off nt
	v_lshlrev_b32_e32 v80, 2, v134
	v_lshl_add_u64 v[82:83], v[164:165], 0, v[80:81]
	global_load_dwordx4 v[200:203], v[82:83], off nt
	v_lshlrev_b32_e32 v80, 2, v136
	v_lshl_add_u64 v[82:83], v[164:165], 0, v[80:81]
	global_load_dwordx4 v[204:207], v[82:83], off nt
	v_lshlrev_b32_e32 v80, 2, v138
	v_lshl_add_u64 v[82:83], v[164:165], 0, v[80:81]
	global_load_dwordx4 v[208:211], v[82:83], off nt
	v_lshlrev_b32_e32 v80, 2, v140
	v_lshl_add_u64 v[82:83], v[164:165], 0, v[80:81]
	global_load_dwordx4 v[220:223], v[82:83], off nt
	v_lshlrev_b32_e32 v80, 2, v142
	v_lshl_add_u64 v[82:83], v[164:165], 0, v[80:81]
	global_load_dwordx4 v[224:227], v[82:83], off nt
	v_lshlrev_b32_e32 v80, 2, v144
	v_lshl_add_u64 v[82:83], v[164:165], 0, v[80:81]
	global_load_dwordx4 v[228:231], v[82:83], off nt
	v_lshlrev_b32_e32 v80, 2, v146
	v_lshl_add_u64 v[82:83], v[164:165], 0, v[80:81]
	global_load_dwordx4 v[232:235], v[82:83], off nt
	s_waitcnt vmcnt(14)
	v_cvt_pk_bf16_f32 v58, v58, v59
	v_cvt_pk_bf16_f32 v59, v60, v61
	v_cvt_pk_bf16_f32 v10, v10, v11
	v_cvt_pk_bf16_f32 v11, v12, v13
	ds_write2_b64 v173, v[58:59], v[10:11] offset0:0 offset1:8
	s_waitcnt vmcnt(12)
	v_cvt_pk_bf16_f32 v62, v62, v63
	v_cvt_pk_bf16_f32 v63, v64, v65
	v_cvt_pk_bf16_f32 v20, v20, v21
	v_cvt_pk_bf16_f32 v21, v22, v23
	ds_write2_b64 v173, v[62:63], v[20:21] offset0:16 offset1:24
	s_waitcnt vmcnt(10)
	v_cvt_pk_bf16_f32 v66, v66, v67
	v_cvt_pk_bf16_f32 v67, v68, v69
	v_cvt_pk_bf16_f32 v14, v14, v15
	v_cvt_pk_bf16_f32 v15, v16, v17
	ds_write2_b64 v173, v[66:67], v[14:15] offset0:32 offset1:40
	s_waitcnt vmcnt(8)
	v_cvt_pk_bf16_f32 v74, v74, v75
	v_cvt_pk_bf16_f32 v75, v76, v77
	v_cvt_pk_bf16_f32 v70, v70, v71
	v_cvt_pk_bf16_f32 v71, v72, v73
	ds_write2_b64 v173, v[74:75], v[70:71] offset0:48 offset1:56
	v_lshlrev_b32_e32 v80, 2, v116
	v_lshl_add_u64 v[82:83], v[78:79], 0, v[80:81]
	global_load_dwordx4 v[58:61], v[82:83], off nt
	v_lshlrev_b32_e32 v80, 2, v118
	v_lshl_add_u64 v[82:83], v[78:79], 0, v[80:81]
	global_load_dwordx4 v[10:13], v[82:83], off nt
	v_lshlrev_b32_e32 v80, 2, v120
	v_lshl_add_u64 v[82:83], v[78:79], 0, v[80:81]
	global_load_dwordx4 v[62:65], v[82:83], off nt
	v_lshlrev_b32_e32 v80, 2, v122
	v_lshl_add_u64 v[82:83], v[78:79], 0, v[80:81]
	global_load_dwordx4 v[20:23], v[82:83], off nt
	v_lshlrev_b32_e32 v80, 2, v124
	v_lshl_add_u64 v[82:83], v[78:79], 0, v[80:81]
	global_load_dwordx4 v[66:69], v[82:83], off nt
	v_lshlrev_b32_e32 v80, 2, v126
	v_lshl_add_u64 v[82:83], v[78:79], 0, v[80:81]
	global_load_dwordx4 v[14:17], v[82:83], off nt
	v_lshlrev_b32_e32 v80, 2, v128
	v_lshl_add_u64 v[82:83], v[78:79], 0, v[80:81]
	global_load_dwordx4 v[74:77], v[82:83], off nt
	v_lshlrev_b32_e32 v80, 2, v130
	v_lshl_add_u64 v[82:83], v[78:79], 0, v[80:81]
	global_load_dwordx4 v[70:73], v[82:83], off nt
	s_waitcnt vmcnt(14)
	v_cvt_pk_bf16_f32 v196, v196, v197
	v_cvt_pk_bf16_f32 v197, v198, v199
	v_cvt_pk_bf16_f32 v200, v200, v201
	v_cvt_pk_bf16_f32 v201, v202, v203
	ds_write2_b64 v173, v[196:197], v[200:201] offset0:64 offset1:72
	s_waitcnt vmcnt(12)
	v_cvt_pk_bf16_f32 v204, v204, v205
	v_cvt_pk_bf16_f32 v205, v206, v207
	v_cvt_pk_bf16_f32 v208, v208, v209
	v_cvt_pk_bf16_f32 v209, v210, v211
	ds_write2_b64 v173, v[204:205], v[208:209] offset0:80 offset1:88
	s_waitcnt vmcnt(10)
	v_cvt_pk_bf16_f32 v220, v220, v221
	v_cvt_pk_bf16_f32 v221, v222, v223
	v_cvt_pk_bf16_f32 v224, v224, v225
	v_cvt_pk_bf16_f32 v225, v226, v227
	ds_write2_b64 v173, v[220:221], v[224:225] offset0:96 offset1:104
	s_waitcnt vmcnt(8)
	v_cvt_pk_bf16_f32 v228, v228, v229
	v_cvt_pk_bf16_f32 v229, v230, v231
	v_cvt_pk_bf16_f32 v232, v232, v233
	v_cvt_pk_bf16_f32 v233, v234, v235
	ds_write2_b64 v173, v[228:229], v[232:233] offset0:112 offset1:120
	v_lshlrev_b32_e32 v80, 2, v132
	v_lshl_add_u64 v[82:83], v[78:79], 0, v[80:81]
	global_load_dwordx4 v[196:199], v[82:83], off nt
	v_lshlrev_b32_e32 v80, 2, v134
	v_lshl_add_u64 v[82:83], v[78:79], 0, v[80:81]
	global_load_dwordx4 v[200:203], v[82:83], off nt
	v_lshlrev_b32_e32 v80, 2, v136
	v_lshl_add_u64 v[82:83], v[78:79], 0, v[80:81]
	global_load_dwordx4 v[204:207], v[82:83], off nt
	v_lshlrev_b32_e32 v80, 2, v138
	v_lshl_add_u64 v[82:83], v[78:79], 0, v[80:81]
	global_load_dwordx4 v[208:211], v[82:83], off nt
	v_lshlrev_b32_e32 v80, 2, v140
	v_lshl_add_u64 v[82:83], v[78:79], 0, v[80:81]
	global_load_dwordx4 v[220:223], v[82:83], off nt
	v_lshlrev_b32_e32 v80, 2, v142
	v_lshl_add_u64 v[82:83], v[78:79], 0, v[80:81]
	global_load_dwordx4 v[224:227], v[82:83], off nt
	v_lshlrev_b32_e32 v80, 2, v144
	v_lshl_add_u64 v[82:83], v[78:79], 0, v[80:81]
	global_load_dwordx4 v[228:231], v[82:83], off nt
	v_lshlrev_b32_e32 v80, 2, v146
	v_lshl_add_u64 v[82:83], v[78:79], 0, v[80:81]
	global_load_dwordx4 v[232:235], v[82:83], off nt
	v_add_u32_e32 v84, 0x2000, v174
	v_add_u32_e32 v85, 0x2800, v174
	s_waitcnt vmcnt(14)
	v_cvt_pk_bf16_f32 v58, v58, v59
	v_cvt_pk_bf16_f32 v59, v60, v61
	v_cvt_pk_bf16_f32 v10, v10, v11
	v_cvt_pk_bf16_f32 v11, v12, v13
	ds_write2_b64 v84, v[58:59], v[10:11] offset0:0 offset1:32
	s_waitcnt vmcnt(12)
	v_cvt_pk_bf16_f32 v62, v62, v63
	v_cvt_pk_bf16_f32 v63, v64, v65
	v_cvt_pk_bf16_f32 v20, v20, v21
	v_cvt_pk_bf16_f32 v21, v22, v23
	ds_write2_b64 v84, v[62:63], v[20:21] offset0:64 offset1:96
	s_waitcnt vmcnt(10)
	v_cvt_pk_bf16_f32 v66, v66, v67
	v_cvt_pk_bf16_f32 v67, v68, v69
	v_cvt_pk_bf16_f32 v14, v14, v15
	v_cvt_pk_bf16_f32 v15, v16, v17
	ds_write2_b64 v84, v[66:67], v[14:15] offset0:128 offset1:160
	s_waitcnt vmcnt(8)
	v_cvt_pk_bf16_f32 v74, v74, v75
	v_cvt_pk_bf16_f32 v75, v76, v77
	v_cvt_pk_bf16_f32 v70, v70, v71
	v_cvt_pk_bf16_f32 v71, v72, v73
	ds_write2_b64 v84, v[74:75], v[70:71] offset0:192 offset1:224
	s_waitcnt vmcnt(6)
	v_cvt_pk_bf16_f32 v196, v196, v197
	v_cvt_pk_bf16_f32 v197, v198, v199
	v_cvt_pk_bf16_f32 v200, v200, v201
	v_cvt_pk_bf16_f32 v201, v202, v203
	ds_write2_b64 v85, v[196:197], v[200:201] offset0:0 offset1:32
	s_waitcnt vmcnt(4)
	v_cvt_pk_bf16_f32 v204, v204, v205
	v_cvt_pk_bf16_f32 v205, v206, v207
	v_cvt_pk_bf16_f32 v208, v208, v209
	v_cvt_pk_bf16_f32 v209, v210, v211
	ds_write2_b64 v85, v[204:205], v[208:209] offset0:64 offset1:96
	s_waitcnt vmcnt(2)
	v_cvt_pk_bf16_f32 v220, v220, v221
	v_cvt_pk_bf16_f32 v221, v222, v223
	v_cvt_pk_bf16_f32 v224, v224, v225
	v_cvt_pk_bf16_f32 v225, v226, v227
	ds_write2_b64 v85, v[220:221], v[224:225] offset0:128 offset1:160
	s_waitcnt vmcnt(0)
	v_cvt_pk_bf16_f32 v228, v228, v229
	v_cvt_pk_bf16_f32 v229, v230, v231
	v_cvt_pk_bf16_f32 v232, v232, v233
	v_cvt_pk_bf16_f32 v233, v234, v235
	ds_write2_b64 v85, v[228:229], v[232:233] offset0:192 offset1:224
	s_branch .Lsjoin_l0

; #define ATT_LDS_WAIT() asm volatile("s_waitcnt lgkmcnt(0)" ::: "memory")
; template <int TYPE>
; __device__ __forceinline__ void sample_unit(const Args& a, int l, int b, int h, LAS unsigned char* lds) {
;     ...
;     for (int rnd = 0; rnd < 9; ++rnd) {
;         const int gidx = rnd * 8 + 7 - wid; const bool valid = gidx <= 64, isnew = gidx == 0; const int ct = 64 - gidx;
;         const float* ksrc = isnew ? kn : kc + (size_t)ct * 64 * W; const float* vsrc = isnew ? vn : vc + (size_t)ct * 64 * W;
;         const int nrows = isnew ? DT : 64;
;         if (TYPE == 0) {
;             if (valid) {
;                 ATT_LDS_WAIT();
;                 ATT_STAGE(ksrc, nrows, false); ATT_STAGE(vsrc, nrows, true);
;                 ATT_LDS_WAIT();
;                 const float* ckt = ckb + (isnew ? PAST : ct * 64) + 4 * hi;
;                 fox_tile(st, (lds_cptr)kreg, vp, qr, ckt, isnew, !started, qlim_new, r32, hi, wsf);
.LBB0_1095:
	s_add_i32 s2, s63, s68
	s_cmp_gt_i32 s2, 64
	s_cbranch_scc1 .LBB0_1094
	s_cmp_eq_u32 s2, 0
	s_cselect_b64 s[54:55], -1, 0
	s_cbranch_scc0 .Lsfast_l1
	s_and_b64 s[2:3], s[54:55], exec
	s_cselect_b32 s3, s60, s65
	s_cselect_b32 s2, s59, s64
	v_lshlrev_b32_e32 v4, 2, v112
	v_lshl_add_u64 v[164:165], s[2:3], 0, v[4:5]
	v_lshlrev_b32_e32 v78, 2, v116
	v_mov_b32_e32 v79, v5
	v_lshlrev_b32_e32 v82, 2, v118
	v_mov_b32_e32 v83, v5
	s_waitcnt lgkmcnt(0)
	v_lshl_add_u64 v[2:3], v[164:165], 0, v[78:79]
	v_lshl_add_u64 v[10:11], v[164:165], 0, v[82:83]
	v_lshlrev_b32_e32 v84, 2, v120
	v_mov_b32_e32 v85, v5
	global_load_dwordx4 v[58:61], v[2:3], off nt
	s_nop 0
	global_load_dwordx4 v[10:13], v[10:11], off nt
	v_lshl_add_u64 v[2:3], v[164:165], 0, v[84:85]
	v_lshlrev_b32_e32 v88, 2, v122
	v_mov_b32_e32 v89, v5
	v_lshl_add_u64 v[14:15], v[164:165], 0, v[88:89]
	global_load_dwordx4 v[62:65], v[2:3], off nt
	global_load_dwordx4 v[20:23], v[14:15], off nt
	s_cselect_b32 s33, 16, 64
	v_cmp_gt_u32_e32 vcc, s33, v133
	v_mov_b32_e32 v14, 0
	v_lshlrev_b32_e32 v2, 2, v124
	v_mov_b32_e32 v66, 0
	v_mov_b32_e32 v67, 0
	v_mov_b32_e32 v68, 0
	v_mov_b32_e32 v69, 0
	s_and_saveexec_b64 s[2:3], vcc
	s_cbranch_execz .LBB0_1098
	v_mov_b32_e32 v3, v5
	v_lshl_add_u64 v[16:17], v[164:165], 0, v[2:3]
	global_load_dwordx4 v[66:69], v[16:17], off nt

; __device__ __forceinline__ int crow(int r, int hi) { return (r & 3) + 8 * (r >> 2) + 4 * hi; }
;     bf16x8 kf[8]; kfrags(kf, kslot, r32, hi);
;     f32x16 p0, p1;
; #pragma unroll
;     for (int g = 0; g < 4; ++g) { const f32x4 c0 = ld4(ckt + 8 * g), c1 = ld4(ckt + 32 + 8 * g);
; #pragma unroll
;         for (int i = 0; i < 4; ++i) { p0[4 * g + i] = c0[i]; p1[4 * g + i] = c1[i]; } }
;     u32x4 kn = {0u, 0xBF800000u, 0xBF80BF80u, 0u}; if (hi) { kn.y = 0u; kn.z = 0u; }
;     const bf16x8 kneg = __builtin_bit_cast(bf16x8, kn);
;     p0 = __builtin_amdgcn_mfma_f32_32x32x16_bf16(kneg, st.mq, p0, 0, 0, 0);
;     p1 = __builtin_amdgcn_mfma_f32_32x32x16_bf16(kneg, st.mq, p1, 0, 0, 0);
; #pragma unroll
;     for (int d0 = 0; d0 < 4; ++d0) {
;         p0 = __builtin_amdgcn_mfma_f32_32x32x16_bf16(kf[2 * d0], qr[d0], p0, 0, 0, 0);
;         p1 = __builtin_amdgcn_mfma_f32_32x32x16_bf16(kf[2 * d0 + 1], qr[d0], p1, 0, 0, 0);
;     }
;     __builtin_amdgcn_sched_barrier(0);
;     if (LEVEL == 2) { asm volatile("" :: "v"(p0), "v"(p1)); return; }
;     if (masked) {
;         asm volatile("; masked tile" ::: "memory");
; #pragma unroll
;         for (int r = 0; r < 16; ++r) { const int kv = crow(r, hi); if (kv >= qlim) p0[r] = NEG; if (kv + 32 >= qlim) p1[r] = NEG; }
.Lsjoin_l1:
	s_ashr_i32 s51, s50, 31
	s_waitcnt lgkmcnt(0)
	v_lshl_add_u64 v[2:3], s[50:51], 2, v[114:115]
	global_load_dwordx4 v[74:77], v[2:3], off
	global_load_dwordx4 v[78:81], v[2:3], off offset:32
	global_load_dwordx4 v[82:85], v[2:3], off offset:64
	global_load_dwordx4 v[86:89], v[2:3], off offset:96
	global_load_dwordx4 v[58:61], v[2:3], off offset:128
	global_load_dwordx4 v[62:65], v[2:3], off offset:160
	global_load_dwordx4 v[66:69], v[2:3], off offset:192
	global_load_dwordx4 v[70:73], v[2:3], off offset:224
	ds_read_b128 v[10:13], v171
	s_waitcnt vmcnt(4)
	v_mfma_f32_32x32x16_bf16 v[74:89], v[90:93], v[6:9], v[74:89]
	s_waitcnt lgkmcnt(0)
	v_mfma_f32_32x32x16_bf16 v[74:89], v[10:13], v[94:97], v[74:89]
	ds_read_b128 v[10:13], v171 offset:512
	s_waitcnt vmcnt(0)
	v_mfma_f32_32x32x16_bf16 v[58:73], v[90:93], v[6:9], v[58:73]
	s_waitcnt lgkmcnt(0)
	v_mfma_f32_32x32x16_bf16 v[58:73], v[10:13], v[94:97], v[58:73]
	ds_read_b128 v[10:13], v171 offset:2048
	s_waitcnt lgkmcnt(0)
	v_mfma_f32_32x32x16_bf16 v[74:89], v[10:13], v[98:101], v[74:89]
	ds_read_b128 v[10:13], v171 offset:2560
	s_waitcnt lgkmcnt(0)
	v_mfma_f32_32x32x16_bf16 v[58:73], v[10:13], v[98:101], v[58:73]
	ds_read_b128 v[10:13], v171 offset:4096
	s_waitcnt lgkmcnt(0)
	v_mfma_f32_32x32x16_bf16 v[74:89], v[10:13], v[102:105], v[74:89]
	ds_read_b128 v[10:13], v171 offset:4608
	s_waitcnt lgkmcnt(0)
	v_mfma_f32_32x32x16_bf16 v[58:73], v[10:13], v[102:105], v[58:73]
	ds_read_b128 v[10:13], v171 offset:6144
	s_waitcnt lgkmcnt(0)
	v_mfma_f32_32x32x16_bf16 v[74:89], v[10:13], v[106:109], v[74:89]
	ds_read_b128 v[10:13], v171 offset:6656
	s_waitcnt lgkmcnt(0)
	v_mfma_f32_32x32x16_bf16 v[58:73], v[10:13], v[106:109], v[58:73]
	s_and_b64 vcc, exec, s[54:55]
	s_cbranch_vccz .LBB0_1146
	s_nop 6
	v_cndmask_b32_e64 v2, v74, v18, s[8:9]
	v_cndmask_b32_e64 v2, v2, v74, s[10:11]
	v_cndmask_b32_e64 v3, v18, v75, s[10:11]
	v_mov_b32_e32 v24, v18
	v_mov_b32_e32 v25, v18
	v_cndmask_b32_e64 v17, v81, v18, s[12:13]
	v_cndmask_b32_e64 v11, v75, v3, s[22:23]
	v_cndmask_b32_e64 v10, v74, v2, s[22:23]
	v_cndmask_b32_e64 v16, v80, v18, s[14:15]
	v_cndmask_b32_e64 v15, v79, v18, s[16:17]
	v_cndmask_b32_e64 v14, v78, v18, s[18:19]
	v_cndmask_b32_e64 v13, v77, v18, s[20:21]
	v_cndmask_b32_e64 v12, v76, v18, s[22:23]
	v_mov_b32_e32 v19, v18
	v_mov_b32_e32 v20, v18
	v_mov_b32_e32 v21, v18
	v_mov_b32_e32 v22, v18
	v_mov_b32_e32 v23, v18
	v_mov_b64_e32 v[88:89], v[24:25]
	v_mov_b32_e32 v58, v18
	v_mov_b32_e32 v59, v18
	v_mov_b32_e32 v60, v18
	v_mov_b32_e32 v61, v18
	v_mov_b32_e32 v62, v18
	v_mov_b32_e32 v63, v18
	v_mov_b32_e32 v64, v18
	v_mov_b32_e32 v65, v18
	v_mov_b32_e32 v66, v18
	v_mov_b32_e32 v67, v18
	v_mov_b32_e32 v68, v18
	v_mov_b32_e32 v69, v18
	v_mov_b32_e32 v70, v18
	v_mov_b32_e32 v71, v18
	v_mov_b32_e32 v72, v18
	v_mov_b32_e32 v73, v18
	v_mov_b64_e32 v[86:87], v[22:23]
	v_mov_b64_e32 v[84:85], v[20:21]
	v_mov_b64_e32 v[82:83], v[18:19]
	v_mov_b64_e32 v[80:81], v[16:17]
	v_mov_b64_e32 v[78:79], v[14:15]
	v_mov_b64_e32 v[76:77], v[12:13]
	v_mov_b64_e32 v[74:75], v[10:11]
